# prefetched FoX/MLA/SWA units skip the prologue workgroup barrier
# speedup vs baseline: 1.0048x; 1.0048x over previous
.Lpf2_w0:
	s_cmp_lg_u32 s32, 0
	s_cbranch_scc1 .Lpf2_wb
	s_waitcnt vmcnt(0) lgkmcnt(0)
	s_barrier
.Lpf2_wb:
	s_mov_b32 s32, 0
	s_waitcnt lgkmcnt(0)
	v_cmp_gt_i32_e64 s[46:47], v1, v4
	v_cmp_gt_i32_e64 s[48:49], v2, v4
	v_cmp_gt_i32_e64 s[50:51], v3, v4
	v_cmp_gt_i32_e64 s[52:53], v5, v4
	v_cmp_gt_i32_e64 s[54:55], v7, v4
	v_cmp_gt_i32_e64 s[56:57], v8, v4
	v_cmp_gt_i32_e64 s[58:59], v9, v4
	v_cmp_gt_i32_e64 s[60:61], v10, v4
	v_cmp_gt_i32_e64 s[62:63], v11, v4
	v_cmp_gt_i32_e64 s[64:65], v12, v4
	v_cmp_gt_i32_e64 s[66:67], v13, v4
	v_cmp_gt_i32_e64 s[68:69], v14, v4
	v_cmp_gt_i32_e64 s[70:71], v15, v4
	v_cmp_gt_i32_e64 s[72:73], v16, v4
	v_cmp_gt_i32_e64 s[74:75], v0, v4
	v_cmp_gt_i32_e64 s[76:77], v31, v4
	v_cmp_gt_i32_e64 s[78:79], v30, v4
	v_cmp_gt_i32_e64 s[80:81], v29, v4
	v_cmp_gt_i32_e64 s[82:83], v28, v4
	v_cmp_gt_i32_e64 s[84:85], v27, v4
	v_cmp_gt_i32_e64 s[86:87], v26, v4
	v_cmp_gt_i32_e64 s[88:89], v25, v4
	v_cmp_gt_i32_e64 s[90:91], v24, v4
	v_cmp_gt_i32_e64 s[92:93], v23, v4
	v_cmp_gt_i32_e64 s[94:95], v22, v4
	v_cmp_gt_i32_e64 s[96:97], v21, v4
	v_cmp_gt_i32_e64 s[98:99], v20, v4
	v_cmp_gt_i32_e64 s[38:39], v19, v4
	v_cmp_gt_i32_e64 s[4:5], v18, v4
	v_cmp_gt_i32_e64 s[6:7], v17, v4
	v_mov_b64_e32 v[16:17], v[192:193]
	v_mov_b64_e32 v[0:1], v[192:193]
	v_mov_b32_e32 v33, v32
	v_mov_b32_e32 v34, v32
	v_mov_b32_e32 v35, v32
	v_mov_b32_e32 v36, v32
	v_mov_b32_e32 v37, v32
	v_mov_b32_e32 v38, v32
	v_mov_b32_e32 v39, v32
	v_mov_b32_e32 v40, v32
	v_mov_b32_e32 v41, v32
	v_mov_b32_e32 v42, v32
	v_mov_b32_e32 v43, v32
	v_mov_b32_e32 v44, v32
	v_mov_b32_e32 v45, v32
	v_mov_b32_e32 v46, v32
	v_mov_b32_e32 v47, v32
	v_mov_b64_e32 v[18:19], v[194:195]
	v_mov_b64_e32 v[20:21], v[196:197]
	v_mov_b64_e32 v[22:23], v[198:199]
	v_mov_b64_e32 v[24:25], v[200:201]
	v_mov_b64_e32 v[26:27], v[202:203]
	v_mov_b64_e32 v[28:29], v[204:205]
	v_mov_b64_e32 v[30:31], v[206:207]
	v_mov_b64_e32 v[2:3], v[194:195]
	v_mov_b64_e32 v[4:5], v[196:197]
	v_mov_b64_e32 v[6:7], v[198:199]
	v_mov_b64_e32 v[8:9], v[200:201]
	v_mov_b64_e32 v[10:11], v[202:203]
	v_mov_b64_e32 v[12:13], v[204:205]
	v_mov_b64_e32 v[14:15], v[206:207]
	s_branch .LBB0_243

.Lpf1_wb:
	s_mov_b32 s32, 0
	s_waitcnt lgkmcnt(0)
	s_cmp_lt_i32 s21, 1
	s_cbranch_scc1 .LBB0_289
	s_add_i32 s12, s28, 1
	v_cvt_f32_i32_e32 v5, s12
	v_cvt_f32_u32_e32 v142, v3
	s_lshr_b32 s4, s4, 1
	v_lshlrev_b32_e32 v1, 4, v1
	v_exp_f32_e64 v3, -v5
	v_lshlrev_b32_e32 v2, 10, v2
	v_mov_b32_e32 v192, v193
	s_or_b32 s29, s4, s5
	v_mul_f32_e32 v132, 0x3fb8aa3b, v3
	v_lshlrev_b32_e32 v3, 1, v0
	v_lshrrev_b32_e32 v0, 2, v0
	v_and_or_b32 v0, v0, 3, v136
	v_and_b32_e32 v3, 32, v3
	v_lshl_add_u32 v0, v0, 6, 0
	v_add3_u32 v145, 0, v2, v1
	v_add3_u32 v147, v0, v3, v4
	v_mov_b32_e32 v194, v193
	v_mov_b32_e32 v195, v193
	v_mov_b32_e32 v196, v193
	v_mov_b32_e32 v197, v193
	v_mov_b32_e32 v198, v193
	v_mov_b32_e32 v199, v193
	v_mov_b32_e32 v200, v193
	v_mov_b32_e32 v201, v193
	v_mov_b32_e32 v202, v193
	v_mov_b32_e32 v203, v193
	v_mov_b32_e32 v204, v193
	v_mov_b32_e32 v205, v193
	v_mov_b32_e32 v206, v193
	v_mov_b32_e32 v207, v193
	v_mov_b64_e32 v[16:17], v[192:193]
	v_mov_b64_e32 v[0:1], v[192:193]
	v_mov_b32_e32 v33, v32
	v_mov_b32_e32 v34, v32
	v_sub_u32_e64 v144, s29, 2 clamp
	v_mov_b32_e32 v35, v32
	v_mov_b32_e32 v36, v32
	v_mov_b32_e32 v37, v32
	v_mov_b32_e32 v38, v32
	v_mov_b32_e32 v39, v32
	v_mov_b32_e32 v40, v32
	v_mov_b32_e32 v41, v32
	v_mov_b32_e32 v42, v32
	v_mov_b32_e32 v43, v32
	v_mov_b32_e32 v44, v32
	v_mov_b32_e32 v45, v32
	v_mov_b32_e32 v46, v32
	v_mov_b32_e32 v47, v32
	s_or_b32 s34, s18, 1
	v_mov_b32_e32 v133, v132
	s_mov_b32 s36, 0
	v_mov_b32_e32 v143, 0
	v_mov_b64_e32 v[18:19], v[194:195]
	v_mov_b64_e32 v[20:21], v[196:197]
	v_mov_b64_e32 v[22:23], v[198:199]
	v_mov_b64_e32 v[24:25], v[200:201]
	v_mov_b64_e32 v[26:27], v[202:203]
	v_mov_b64_e32 v[28:29], v[204:205]
	v_mov_b64_e32 v[30:31], v[206:207]
	v_mov_b64_e32 v[2:3], v[194:195]
	v_mov_b64_e32 v[4:5], v[196:197]
	v_mov_b64_e32 v[6:7], v[198:199]
	v_mov_b64_e32 v[8:9], v[200:201]
	v_mov_b64_e32 v[10:11], v[202:203]
	v_mov_b64_e32 v[12:13], v[204:205]
	v_mov_b64_e32 v[14:15], v[206:207]
	v_mov_b32_e32 v141, 0
	s_branch .LBB0_280

.Lpf0_w0:
	v_pk_fma_f32 v[12:13], v[22:23], v[6:7], v[12:13] neg_lo:[0,0,1] neg_hi:[0,0,1]
	v_pk_mul_f32 v[6:7], v[30:31], v[6:7]
	v_cvt_pk_bf16_f32 v81, v12, v13
	v_pk_fma_f32 v[6:7], v[22:23], v[8:9], v[6:7]
	v_lshlrev_b32_e32 v8, 16, v14
	v_and_b32_e32 v9, 0xffff0000, v14
	v_cvt_pk_bf16_f32 v85, v6, v7
	v_lshlrev_b32_e32 v6, 16, v10
	v_and_b32_e32 v7, 0xffff0000, v10
	v_pk_mul_f32 v[12:13], v[24:25], v[8:9]
	s_nop 0
	v_pk_fma_f32 v[12:13], v[16:17], v[6:7], v[12:13] neg_lo:[0,0,1] neg_hi:[0,0,1]
	v_pk_mul_f32 v[6:7], v[24:25], v[6:7]
	v_cvt_pk_bf16_f32 v82, v12, v13
	v_pk_fma_f32 v[6:7], v[16:17], v[8:9], v[6:7]
	v_lshlrev_b32_e32 v8, 16, v15
	v_and_b32_e32 v9, 0xffff0000, v15
	v_cvt_pk_bf16_f32 v86, v6, v7
	v_lshlrev_b32_e32 v6, 16, v11
	v_and_b32_e32 v7, 0xffff0000, v11
	v_pk_mul_f32 v[10:11], v[26:27], v[8:9]
	s_nop 0
	v_pk_fma_f32 v[10:11], v[18:19], v[6:7], v[10:11] neg_lo:[0,0,1] neg_hi:[0,0,1]
	v_pk_mul_f32 v[6:7], v[26:27], v[6:7]
	v_cvt_pk_bf16_f32 v83, v10, v11
	v_pk_fma_f32 v[6:7], v[18:19], v[8:9], v[6:7]
	v_mov_b64_e32 v[16:17], v[192:193]
	v_cvt_pk_bf16_f32 v87, v6, v7
	s_cmp_lg_u32 s32, 0
	s_cbranch_scc1 .Lpf0_wb
	s_waitcnt vmcnt(0) lgkmcnt(0)
	s_barrier
.Lpf0_wb:
	s_mov_b32 s32, 0
	s_waitcnt lgkmcnt(0)
	v_mov_b64_e32 v[18:19], v[194:195]
	v_lshlrev_b32_e32 v0, 10, v5
	v_add3_u32 v137, 0, v0, v1
	v_lshl_add_u32 v0, v4, 6, 0
	v_add3_u32 v147, v0, v2, v3
	v_mov_b64_e32 v[0:1], v[192:193]
	v_mov_b32_e32 v33, v32
	v_mov_b32_e32 v34, v32
	v_mov_b32_e32 v35, v32
	v_mov_b32_e32 v36, v32
	v_mov_b32_e32 v37, v32
	v_mov_b32_e32 v38, v32
	v_mov_b32_e32 v39, v32
	v_mov_b32_e32 v40, v32
	v_mov_b32_e32 v41, v32
	v_mov_b32_e32 v42, v32
	v_mov_b32_e32 v43, v32
	v_mov_b32_e32 v44, v32
	v_mov_b32_e32 v45, v32
	v_mov_b32_e32 v46, v32
	v_mov_b32_e32 v47, v32
	v_mov_b64_e32 v[20:21], v[196:197]
	v_mov_b64_e32 v[22:23], v[198:199]
	v_mov_b64_e32 v[24:25], v[200:201]
	v_mov_b64_e32 v[26:27], v[202:203]
	v_mov_b64_e32 v[28:29], v[204:205]
	v_mov_b64_e32 v[30:31], v[206:207]
	v_mov_b64_e32 v[2:3], v[194:195]
	v_mov_b64_e32 v[4:5], v[196:197]
	v_mov_b64_e32 v[6:7], v[198:199]
	v_mov_b64_e32 v[8:9], v[200:201]
	v_mov_b64_e32 v[10:11], v[202:203]
	v_mov_b64_e32 v[12:13], v[204:205]
	v_mov_b64_e32 v[14:15], v[206:207]
	s_branch .LBB0_297
